# v63 + MLA softmax section: first P.V MFMA three VALU slots earlier (group 0 packed out of place into v[154:157]; its row-sum adds after the first two MFMAs)
# speedup vs baseline: 1.0014x; 1.0014x over previous
.LBB0_1482:
	v_exp_f32_e32 v66, v66
	v_exp_f32_e32 v67, v67
	v_exp_f32_e32 v68, v68
	v_exp_f32_e32 v69, v69
	v_exp_f32_e32 v70, v70
	v_exp_f32_e32 v71, v71
	v_exp_f32_e32 v72, v72
	v_exp_f32_e32 v73, v73
	v_cvt_pk_bf16_f32 v154, v66, v67
	v_cvt_pk_bf16_f32 v155, v68, v69
	v_cvt_pk_bf16_f32 v156, v70, v71
	v_cvt_pk_bf16_f32 v157, v72, v73
	v_exp_f32_e32 v74, v74
	v_exp_f32_e32 v75, v75
	v_mfma_f32_32x32x16_bf16 v[18:33], v[154:157], v[150:153], v[18:33]
	v_exp_f32_e32 v76, v76
	v_exp_f32_e32 v77, v77
	v_exp_f32_e32 v78, v78
	s_waitcnt lgkmcnt(6)
	v_mfma_f32_32x32x16_bf16 v[34:49], v[154:157], v[134:137], v[34:49]
	v_exp_f32_e32 v79, v79
	v_exp_f32_e32 v80, v80
	v_exp_f32_e32 v81, v81
	v_pk_add_f32 v[162:163], v[66:67], v[68:69]
	v_pk_add_f32 v[164:165], v[70:71], v[72:73]
	v_pk_add_f32 v[158:159], v[162:163], v[164:165]
	v_pk_add_f32 v[154:155], v[74:75], v[76:77]
	v_pk_add_f32 v[156:157], v[78:79], v[80:81]
	v_pk_add_f32 v[160:161], v[154:155], v[156:157]
	v_cvt_pk_bf16_f32 v70, v74, v75
	v_cvt_pk_bf16_f32 v71, v76, v77
	v_cvt_pk_bf16_f32 v72, v78, v79
	v_cvt_pk_bf16_f32 v73, v80, v81
	v_exp_f32_e32 v82, v82
	v_exp_f32_e32 v83, v83
	v_mfma_f32_32x32x16_bf16 v[18:33], v[70:73], v[146:149], v[18:33]
	v_exp_f32_e32 v84, v84
	v_exp_f32_e32 v85, v85
	v_exp_f32_e32 v86, v86
	s_waitcnt lgkmcnt(4)
	v_mfma_f32_32x32x16_bf16 v[34:49], v[70:73], v[130:133], v[34:49]
	v_exp_f32_e32 v87, v87
	v_exp_f32_e32 v88, v88
	v_exp_f32_e32 v89, v89
	v_pk_add_f32 v[154:155], v[82:83], v[84:85]
	v_pk_add_f32 v[156:157], v[86:87], v[88:89]
	v_pk_add_f32 v[162:163], v[154:155], v[156:157]
	v_cvt_pk_bf16_f32 v74, v82, v83
	v_cvt_pk_bf16_f32 v75, v84, v85
	v_cvt_pk_bf16_f32 v76, v86, v87
	v_cvt_pk_bf16_f32 v77, v88, v89
	v_exp_f32_e32 v90, v90
	v_exp_f32_e32 v91, v91
	v_mfma_f32_32x32x16_bf16 v[18:33], v[74:77], v[142:145], v[18:33]
	v_exp_f32_e32 v92, v92
	v_exp_f32_e32 v93, v93
	v_exp_f32_e32 v94, v94
	s_waitcnt lgkmcnt(2)
	v_mfma_f32_32x32x16_bf16 v[34:49], v[74:77], v[126:129], v[34:49]
	v_exp_f32_e32 v95, v95
	v_exp_f32_e32 v96, v96
	v_exp_f32_e32 v97, v97
	v_pk_add_f32 v[154:155], v[90:91], v[92:93]
	v_pk_add_f32 v[156:157], v[94:95], v[96:97]
	v_pk_add_f32 v[164:165], v[154:155], v[156:157]
	v_cvt_pk_bf16_f32 v78, v90, v91
	v_cvt_pk_bf16_f32 v79, v92, v93
	v_cvt_pk_bf16_f32 v80, v94, v95
	v_cvt_pk_bf16_f32 v81, v96, v97
	v_pk_add_f32 v[158:159], v[158:159], v[160:161]
	s_add_u32 s24, s24, 0x10000
	s_addc_u32 s25, s25, 0
	v_mfma_f32_32x32x16_bf16 v[18:33], v[78:81], v[138:141], v[18:33]
	v_pk_add_f32 v[162:163], v[162:163], v[164:165]
	s_add_u32 s22, s22, 0x1000
	s_addc_u32 s23, s23, 0
	s_waitcnt lgkmcnt(0)
	v_mfma_f32_32x32x16_bf16 v[34:49], v[78:81], v[122:125], v[34:49]
	v_pk_add_f32 v[158:159], v[158:159], v[162:163]
	v_add_f32_e32 v158, v158, v159
	v_add_u32_e32 v66, s56, v182
	v_add_f32_e32 v173, v173, v158
	v_add_u32_e32 v67, v66, v184
	v_add_u32_e32 v66, v66, v189
	s_cmp_eq_u32 s24, 0x200000
	s_waitcnt vmcnt(0) lgkmcnt(0)
	s_barrier
	ds_read_b128 v[82:85], v67
	s_cbranch_scc1 .LBB0_1484
	s_mov_b32 s49, s57
	s_mul_i32 s52, s49, 0x3000
	s_branch .Lmla2_reads2
